# same as previous best but with the compiler's original V-fragment read distance (2 MFMA gaps)
# speedup vs baseline: 1.0108x; 1.0108x over previous
.LBB0_590:
	s_waitcnt lgkmcnt(2)
	v_mfma_f32_32x32x16_bf16 v[16:31], v[128:131], v[48:51], v[16:31]
	ds_read_b64_tr_b16 v[56:57], v15 offset:2048
	ds_read_b64_tr_b16 v[58:59], v15 offset:3072
	v_mfma_f32_16x16x32_bf16 v[144:147], v[2:5], v[140:143], v[144:147]
	v_exp_f32_e32 v96, v96
	v_exp_f32_e32 v97, v97
	v_exp_f32_e32 v98, v98
	v_exp_f32_e32 v99, v99
	s_waitcnt lgkmcnt(2)
	v_mfma_f32_32x32x16_bf16 v[32:47], v[128:131], v[52:55], v[32:47]
	ds_read_b64_tr_b16 v[48:49], v15 offset:2560
	ds_read_b64_tr_b16 v[50:51], v15 offset:3584
	v_exp_f32_e32 v100, v100
	v_exp_f32_e32 v101, v101
	v_exp_f32_e32 v102, v102
	v_exp_f32_e32 v103, v103
	s_waitcnt lgkmcnt(2)
	v_mfma_f32_32x32x16_bf16 v[16:31], v[10:13], v[56:59], v[16:31]
	ds_read_b64_tr_b16 v[52:53], v15 offset:4096
	ds_read_b64_tr_b16 v[54:55], v15 offset:5120
	v_exp_f32_e32 v104, v104
	v_exp_f32_e32 v105, v105
	v_exp_f32_e32 v106, v106
	v_exp_f32_e32 v107, v107
	s_waitcnt lgkmcnt(2)
	v_mfma_f32_32x32x16_bf16 v[32:47], v[10:13], v[48:51], v[32:47]
	ds_read_b64_tr_b16 v[56:57], v15 offset:4608
	ds_read_b64_tr_b16 v[58:59], v15 offset:5632
	v_exp_f32_e32 v108, v108
	v_exp_f32_e32 v109, v109
	v_exp_f32_e32 v110, v110
	v_exp_f32_e32 v111, v111
	s_waitcnt lgkmcnt(2)
	v_mfma_f32_32x32x16_bf16 v[16:31], v[6:9], v[52:55], v[16:31]
	ds_read_b64_tr_b16 v[10:11], v15 offset:6144
	ds_read_b64_tr_b16 v[12:13], v15 offset:7168
	v_exp_f32_e32 v80, v80
	v_exp_f32_e32 v81, v81
	v_exp_f32_e32 v82, v82
	v_exp_f32_e32 v83, v83
	s_waitcnt lgkmcnt(2)
	v_mfma_f32_32x32x16_bf16 v[32:47], v[6:9], v[56:59], v[32:47]
	ds_read_b64_tr_b16 v[48:49], v15 offset:6656
	ds_read_b64_tr_b16 v[50:51], v15 offset:7680
	v_exp_f32_e32 v84, v84
	v_exp_f32_e32 v85, v85
	v_exp_f32_e32 v86, v86
	v_exp_f32_e32 v87, v87
	s_waitcnt lgkmcnt(2)
	v_mfma_f32_32x32x16_bf16 v[16:31], v[2:5], v[10:13], v[16:31]
	v_exp_f32_e32 v88, v88
	v_exp_f32_e32 v89, v89
	v_exp_f32_e32 v90, v90
	v_exp_f32_e32 v91, v91
	s_waitcnt lgkmcnt(0)
	v_mfma_f32_32x32x16_bf16 v[32:47], v[2:5], v[48:51], v[32:47]
	v_exp_f32_e32 v92, v92
	v_exp_f32_e32 v93, v93
	v_exp_f32_e32 v94, v94
	v_exp_f32_e32 v95, v95
	s_add_i32 s12, s8, -4
	s_add_i32 s13, s8, 1
	s_cmp_gt_i32 s8, 3
	s_cselect_b32 s12, s12, s13
	v_lshl_add_u32 v6, s12, 13, v135
	ds_read_b128 v[2:5], v6
	ds_read_b128 v[6:9], v6 offset:512
	s_cmp_lg_u32 s8, 4
	s_cselect_b32 s54, s13, 0
	v_lshl_add_u32 v15, s54, 13, v135
	v_lshl_add_u32 v128, s8, 14, v1
	s_waitcnt lgkmcnt(1)
	v_mfma_f32_32x32x16_bf16 v[64:79], v[2:5], v[124:127], 0
	ds_read_b128 v[10:13], v15 offset:2048
	v_cvt_pk_bf16_f32 v2, v96, v97
	v_cvt_pk_bf16_f32 v3, v98, v99
	s_nop 0
	ds_read_b128 v[96:99], v15 offset:2560
	v_cvt_pk_bf16_f32 v4, v100, v101
	s_waitcnt lgkmcnt(2)
	v_mfma_f32_32x32x16_bf16 v[48:63], v[6:9], v[124:127], 0
	v_cvt_pk_bf16_f32 v5, v102, v103
	s_waitcnt lgkmcnt(1)
	v_mfma_f32_32x32x16_bf16 v[64:79], v[10:13], v[120:123], v[64:79]
	ds_read_b128 v[6:9], v15 offset:4096
	v_mfma_f32_16x16x32_bf16 v[144:147], v[2:5], v[140:143], v[144:147]
	v_cvt_pk_bf16_f32 v10, v104, v105
	v_cvt_pk_bf16_f32 v11, v106, v107
	s_waitcnt lgkmcnt(1)
	v_mfma_f32_32x32x16_bf16 v[48:63], v[96:99], v[120:123], v[48:63]
	ds_read_b128 v[100:103], v15 offset:4608
	v_cvt_pk_bf16_f32 v12, v108, v109
	v_cvt_pk_bf16_f32 v13, v110, v111
	s_waitcnt lgkmcnt(1)
	v_mfma_f32_32x32x16_bf16 v[64:79], v[6:9], v[116:119], v[64:79]
	ds_read_b128 v[96:99], v15 offset:6144
	v_mfma_f32_16x16x32_bf16 v[144:147], v[10:13], v[140:143], v[144:147]
	v_cvt_pk_bf16_f32 v6, v80, v81
	v_cvt_pk_bf16_f32 v7, v82, v83
	s_waitcnt lgkmcnt(1)
	v_mfma_f32_32x32x16_bf16 v[48:63], v[100:103], v[116:119], v[48:63]
	ds_read_b128 v[80:83], v15 offset:6656
	v_cvt_pk_bf16_f32 v8, v84, v85
	v_cvt_pk_bf16_f32 v9, v86, v87
	s_waitcnt lgkmcnt(1)
	v_mfma_f32_32x32x16_bf16 v[64:79], v[96:99], v[112:115], v[64:79]
	v_cvt_pk_bf16_f32 v84, v88, v89
	v_cvt_pk_bf16_f32 v85, v90, v91
	v_mfma_f32_16x16x32_bf16 v[144:147], v[6:9], v[140:143], v[144:147]
	ds_read_b64_tr_b16 v[88:89], v128
	ds_read_b64_tr_b16 v[90:91], v128 offset:1024
	s_waitcnt lgkmcnt(2)
	v_mfma_f32_32x32x16_bf16 v[48:63], v[80:83], v[112:115], v[48:63]
	v_cvt_pk_bf16_f32 v86, v92, v93
	v_cvt_pk_bf16_f32 v87, v94, v95
	ds_read_b64_tr_b16 v[80:81], v128 offset:512
	ds_read_b64_tr_b16 v[82:83], v128 offset:1536
	s_waitcnt lgkmcnt(2)
	v_mfma_f32_32x32x16_bf16 v[16:31], v[2:5], v[88:91], v[16:31]
	ds_read_b64_tr_b16 v[92:93], v128 offset:2048
	ds_read_b64_tr_b16 v[94:95], v128 offset:3072
	v_mfma_f32_16x16x32_bf16 v[144:147], v[84:87], v[140:143], v[144:147]
	v_exp_f32_e32 v64, v64
	v_exp_f32_e32 v65, v65
	v_exp_f32_e32 v66, v66
	v_exp_f32_e32 v67, v67
	s_waitcnt lgkmcnt(2)
	v_mfma_f32_32x32x16_bf16 v[32:47], v[2:5], v[80:83], v[32:47]
	ds_read_b64_tr_b16 v[88:89], v128 offset:2560
	ds_read_b64_tr_b16 v[90:91], v128 offset:3584
	v_exp_f32_e32 v68, v68
	v_exp_f32_e32 v69, v69
	v_exp_f32_e32 v70, v70
	v_exp_f32_e32 v71, v71
	s_waitcnt lgkmcnt(2)
	v_mfma_f32_32x32x16_bf16 v[16:31], v[10:13], v[92:95], v[16:31]
	ds_read_b64_tr_b16 v[2:3], v128 offset:4096
	ds_read_b64_tr_b16 v[4:5], v128 offset:5120
	v_exp_f32_e32 v72, v72
	v_exp_f32_e32 v73, v73
	v_exp_f32_e32 v74, v74
	v_exp_f32_e32 v75, v75
	s_waitcnt lgkmcnt(2)
	v_mfma_f32_32x32x16_bf16 v[32:47], v[10:13], v[88:91], v[32:47]
	ds_read_b64_tr_b16 v[80:81], v128 offset:4608
	ds_read_b64_tr_b16 v[82:83], v128 offset:5632
	v_exp_f32_e32 v76, v76
	v_exp_f32_e32 v77, v77
	v_exp_f32_e32 v78, v78
	v_exp_f32_e32 v79, v79
	s_waitcnt lgkmcnt(2)
	v_mfma_f32_32x32x16_bf16 v[16:31], v[6:9], v[2:5], v[16:31]
	ds_read_b64_tr_b16 v[10:11], v128 offset:6144
	ds_read_b64_tr_b16 v[12:13], v128 offset:7168
	v_exp_f32_e32 v48, v48
	v_exp_f32_e32 v49, v49
	v_exp_f32_e32 v50, v50
	v_exp_f32_e32 v51, v51
	s_waitcnt lgkmcnt(2)
	v_mfma_f32_32x32x16_bf16 v[32:47], v[6:9], v[80:83], v[32:47]
	ds_read_b64_tr_b16 v[2:3], v128 offset:6656
	ds_read_b64_tr_b16 v[4:5], v128 offset:7680
	v_exp_f32_e32 v52, v52
	v_exp_f32_e32 v53, v53
	v_exp_f32_e32 v54, v54
	v_exp_f32_e32 v55, v55
	s_waitcnt lgkmcnt(2)
	v_mfma_f32_32x32x16_bf16 v[16:31], v[84:87], v[10:13], v[16:31]
	v_exp_f32_e32 v56, v56
	v_exp_f32_e32 v57, v57
	v_exp_f32_e32 v58, v58
	v_exp_f32_e32 v59, v59
	s_waitcnt lgkmcnt(0)
	v_mfma_f32_32x32x16_bf16 v[32:47], v[84:87], v[2:5], v[32:47]
	v_exp_f32_e32 v60, v60
	v_exp_f32_e32 v61, v61
	v_exp_f32_e32 v62, v62
	v_exp_f32_e32 v63, v63
	s_add_i32 s8, s54, 1
	s_cmp_lg_u32 s54, 4
	s_cselect_b32 s8, s8, 0
	s_add_u32 s6, s6, 0x4000
	s_addc_u32 s7, s7, 0
	s_add_u32 s40, s40, 0x4000
	s_waitcnt vmcnt(0) lgkmcnt(0)
	s_barrier
	s_addc_u32 s41, s41, 0
	s_add_i32 s49, s49, 2
	s_cmp_lt_u32 s51, s50
	s_cbranch_scc0 .LBB0_596
